# dilated attention fast path: high-half weight broadcast folded into op_sel (6 v_mov_b32 per iteration removed), on top of permanent splat C block and in-place PV
# baseline (speedup 1.0000x reference)
;     ...
; #pragma unroll
;     for (int r = 0; r < 16; ++r) {
;         float e0 = __builtin_amdgcn_exp2f(p0[r]), e1 = __builtin_amdgcn_exp2f(p1[r]);
;         if (WMODE == 1) { e0 *= wa[r]; e1 *= wa[r]; }
;         if (WMODE == 4) { const int d0 = dlt0 - ((r & 3) + 8 * (r >> 2)), d1 = d0 - 32;
;             const float w0 = (((unsigned)d0 <= 128u) ? 1.f : 0.f) + ((((unsigned)d0 <= 512u) && ((d0 & 3) == 0)) ? 1.f : 0.f) + ((((unsigned)d0 <= 2048u) && ((d0 & 15) == 0)) ? 1.f : 0.f);
;             const float w1 = (((unsigned)d1 <= 128u) ? 1.f : 0.f) + ((((unsigned)d1 <= 512u) && ((d1 & 3) == 0)) ? 1.f : 0.f) + ((((unsigned)d1 <= 2048u) && ((d1 & 15) == 0)) ? 1.f : 0.f);
;             e0 *= w0; e1 *= w1; }
;         p0[r] = e0; p1[r] = e1; s0 += e0; s1 += e1; }
;     l += s0 + s1;
.LBB0_767:
	v_exp_f32_e32 v99, v66
	v_exp_f32_e32 v98, v82
	v_exp_f32_e32 v67, v67
	v_exp_f32_e32 v66, v83
	v_exp_f32_e32 v83, v68
	v_exp_f32_e32 v82, v84
	v_exp_f32_e32 v69, v69
	v_exp_f32_e32 v68, v85
	s_waitcnt lgkmcnt(3)
	v_pk_fma_f32 v[84:85], v[62:63], v[98:99], 0 op_sel_hi:[0,1,0]
	v_pk_mul_f32 v[172:173], v[62:63], v[98:99] op_sel_hi:[0,1]
	v_pk_mul_f32 v[176:177], v[62:63], v[66:67] op_sel:[1,0]
	v_pk_fma_f32 v[62:63], v[62:63], v[66:67], v[84:85] op_sel:[1,0,0]
	v_pk_mul_f32 v[180:181], v[64:65], v[82:83] op_sel_hi:[0,1]
	v_pk_fma_f32 v[62:63], v[64:65], v[82:83], v[62:63] op_sel_hi:[0,1,1]
	v_exp_f32_e32 v67, v70
	v_exp_f32_e32 v66, v86
	v_mov_b32_e32 v64, v65
	v_pk_mul_f32 v[184:185], v[64:65], v[68:69] op_sel_hi:[0,1]
	v_pk_fma_f32 v[62:63], v[64:65], v[68:69], v[62:63] op_sel_hi:[0,1,1]
	v_exp_f32_e32 v65, v71
	v_exp_f32_e32 v64, v87
	v_exp_f32_e32 v69, v72
	v_exp_f32_e32 v68, v88
	v_exp_f32_e32 v71, v73
	v_exp_f32_e32 v70, v89
	v_exp_f32_e32 v73, v74
	v_exp_f32_e32 v72, v90
	s_waitcnt lgkmcnt(2)
	v_pk_fma_f32 v[62:63], v[58:59], v[66:67], v[62:63] op_sel_hi:[0,1,1]
	v_pk_mul_f32 v[188:189], v[58:59], v[66:67] op_sel_hi:[0,1]
	v_exp_f32_e32 v75, v75
	v_exp_f32_e32 v74, v91
	v_pk_mul_f32 v[204:205], v[58:59], v[64:65] op_sel:[1,0]
	v_pk_fma_f32 v[58:59], v[58:59], v[64:65], v[62:63] op_sel:[1,0,0]
	v_exp_f32_e32 v83, v76
	v_exp_f32_e32 v82, v92
	v_pk_mul_f32 v[208:209], v[60:61], v[68:69] op_sel_hi:[0,1]
	v_pk_fma_f32 v[58:59], v[60:61], v[68:69], v[58:59] op_sel_hi:[0,1,1]
	v_exp_f32_e32 v77, v77
	v_exp_f32_e32 v76, v93
	v_pk_fma_f32 v[58:59], v[60:61], v[70:71], v[58:59] op_sel:[1,0,0]
	v_exp_f32_e32 v85, v78
	v_exp_f32_e32 v84, v94
	s_waitcnt lgkmcnt(1)
	v_pk_fma_f32 v[58:59], v[54:55], v[72:73], v[58:59] op_sel_hi:[0,1,1]
	v_exp_f32_e32 v79, v79
	v_exp_f32_e32 v78, v95
	v_pk_mul_f32 v[210:211], v[54:55], v[72:73] op_sel_hi:[0,1]
	v_pk_mul_f32 v[190:191], v[54:55], v[74:75] op_sel:[1,0]
	v_pk_fma_f32 v[54:55], v[54:55], v[74:75], v[58:59] op_sel:[1,0,0]
	v_exp_f32_e32 v87, v80
	v_exp_f32_e32 v86, v96
	v_pk_mul_f32 v[192:193], v[56:57], v[82:83] op_sel_hi:[0,1]
	v_pk_fma_f32 v[54:55], v[56:57], v[82:83], v[54:55] op_sel_hi:[0,1,1]
	v_exp_f32_e32 v81, v81
	v_exp_f32_e32 v80, v97
	v_pk_fma_f32 v[54:55], v[56:57], v[76:77], v[54:55] op_sel:[1,0,0]
	s_waitcnt lgkmcnt(0)
	v_pk_fma_f32 v[54:55], v[50:51], v[84:85], v[54:55] op_sel_hi:[0,1,1]
	v_pk_mul_f32 v[186:187], v[50:51], v[84:85] op_sel_hi:[0,1]
	v_pk_mul_f32 v[174:175], v[50:51], v[78:79] op_sel:[1,0]
	v_pk_fma_f32 v[50:51], v[50:51], v[78:79], v[54:55] op_sel:[1,0,0]
	v_pk_mul_f32 v[178:179], v[52:53], v[86:87] op_sel_hi:[0,1]
	v_pk_fma_f32 v[50:51], v[52:53], v[86:87], v[50:51] op_sel_hi:[0,1,1]
	v_pk_fma_f32 v[50:51], v[52:53], v[80:81], v[50:51] op_sel:[1,0,0]
	v_pk_mul_f32 v[206:207], v[60:61], v[70:71] op_sel:[1,0]
	v_pk_mul_f32 v[182:183], v[56:57], v[76:77] op_sel:[1,0]
	v_pk_mul_f32 v[168:169], v[52:53], v[80:81] op_sel:[1,0]
	v_add_f32_e32 v170, v50, v51
	v_mov_b32_e32 v224, v223
	v_mov_b32_e32 v227, v222

; #define LAS __attribute__((address_space(3)))
;     ...
; #pragma unroll
;     for (int r = 0; r < 16; ++r) {
;         float e0 = __builtin_amdgcn_exp2f(p0[r]), e1 = __builtin_amdgcn_exp2f(p1[r]);
;         if (WMODE == 1) { e0 *= wa[r]; e1 *= wa[r]; }
;         if (WMODE == 4) { const int d0 = dlt0 - ((r & 3) + 8 * (r >> 2)), d1 = d0 - 32;
;             const float w0 = (((unsigned)d0 <= 128u) ? 1.f : 0.f) + ((((unsigned)d0 <= 512u) && ((d0 & 3) == 0)) ? 1.f : 0.f) + ((((unsigned)d0 <= 2048u) && ((d0 & 15) == 0)) ? 1.f : 0.f);
;             const float w1 = (((unsigned)d1 <= 128u) ? 1.f : 0.f) + ((((unsigned)d1 <= 512u) && ((d1 & 3) == 0)) ? 1.f : 0.f) + ((((unsigned)d1 <= 2048u) && ((d1 & 15) == 0)) ? 1.f : 0.f);
;             e0 *= w0; e1 *= w1; }
;         p0[r] = e0; p1[r] = e1; s0 += e0; s1 += e1; }
;     l += s0 + s1;
; template <int MODE> __device__ __forceinline__ void attn_unit(LAS unsigned char* lds, const AttnP& P, int b, int h, int qb) {
;     ...
;                     if (nearb || midb || farb) { f32x16 wm; const LAS f32x4* wp = wml + (nearb ? 0 : (midb ? 256 : 512));
; #pragma unroll
;                         for (int i = 0; i < 4; ++i) { const f32x4 w = wp[i];
; #pragma unroll
;                             for (int j = 0; j < 4; ++j) wm[4 * i + j] = w[j]; }
;                         softmax_step<1, true>(p0, p1, m1, l1, oa0, oa1, first, wm, dlt0, 0.f, &negm1); }
.LBB0_790:
	v_exp_f32_e32 v99, v66
	v_exp_f32_e32 v98, v82
	v_exp_f32_e32 v67, v67
	v_exp_f32_e32 v66, v83
	v_exp_f32_e32 v83, v68
	v_exp_f32_e32 v82, v84
	v_exp_f32_e32 v69, v69
	v_exp_f32_e32 v68, v85
	s_waitcnt lgkmcnt(3)
	v_pk_fma_f32 v[84:85], v[46:47], v[98:99], 0 op_sel_hi:[0,1,0]
	v_pk_mul_f32 v[172:173], v[46:47], v[98:99] op_sel_hi:[0,1]
	v_pk_mul_f32 v[176:177], v[46:47], v[66:67] op_sel:[1,0]
	v_pk_fma_f32 v[46:47], v[46:47], v[66:67], v[84:85] op_sel:[1,0,0]
	v_pk_mul_f32 v[180:181], v[48:49], v[82:83] op_sel_hi:[0,1]
	v_pk_fma_f32 v[46:47], v[48:49], v[82:83], v[46:47] op_sel_hi:[0,1,1]
	v_exp_f32_e32 v67, v70
	v_exp_f32_e32 v66, v86
	v_mov_b32_e32 v48, v49
	v_pk_mul_f32 v[184:185], v[48:49], v[68:69] op_sel_hi:[0,1]
	v_pk_fma_f32 v[46:47], v[48:49], v[68:69], v[46:47] op_sel_hi:[0,1,1]
	v_exp_f32_e32 v49, v71
	v_exp_f32_e32 v48, v87
	v_exp_f32_e32 v69, v72
	v_exp_f32_e32 v68, v88
	v_exp_f32_e32 v71, v73
	v_exp_f32_e32 v70, v89
	v_exp_f32_e32 v73, v74
	v_exp_f32_e32 v72, v90
	s_waitcnt lgkmcnt(2)
	v_pk_fma_f32 v[46:47], v[42:43], v[66:67], v[46:47] op_sel_hi:[0,1,1]
	v_pk_mul_f32 v[188:189], v[42:43], v[66:67] op_sel_hi:[0,1]
	v_exp_f32_e32 v75, v75
	v_exp_f32_e32 v74, v91
	v_pk_mul_f32 v[204:205], v[42:43], v[48:49] op_sel:[1,0]
	v_pk_fma_f32 v[42:43], v[42:43], v[48:49], v[46:47] op_sel:[1,0,0]
	v_exp_f32_e32 v83, v76
	v_exp_f32_e32 v82, v92
	v_pk_mul_f32 v[208:209], v[44:45], v[68:69] op_sel_hi:[0,1]
	v_pk_fma_f32 v[42:43], v[44:45], v[68:69], v[42:43] op_sel_hi:[0,1,1]
	v_exp_f32_e32 v77, v77
	v_exp_f32_e32 v76, v93
	v_pk_fma_f32 v[42:43], v[44:45], v[70:71], v[42:43] op_sel:[1,0,0]
	v_exp_f32_e32 v85, v78
	v_exp_f32_e32 v84, v94
	s_waitcnt lgkmcnt(1)
	v_pk_fma_f32 v[42:43], v[38:39], v[72:73], v[42:43] op_sel_hi:[0,1,1]
	v_exp_f32_e32 v79, v79
	v_exp_f32_e32 v78, v95
	v_pk_mul_f32 v[210:211], v[38:39], v[72:73] op_sel_hi:[0,1]
	v_pk_mul_f32 v[190:191], v[38:39], v[74:75] op_sel:[1,0]
	v_pk_fma_f32 v[38:39], v[38:39], v[74:75], v[42:43] op_sel:[1,0,0]
	v_exp_f32_e32 v87, v80
	v_exp_f32_e32 v86, v96
	v_pk_mul_f32 v[192:193], v[40:41], v[82:83] op_sel_hi:[0,1]
	v_pk_fma_f32 v[38:39], v[40:41], v[82:83], v[38:39] op_sel_hi:[0,1,1]
	v_exp_f32_e32 v81, v81
	v_exp_f32_e32 v80, v97
	v_pk_fma_f32 v[38:39], v[40:41], v[76:77], v[38:39] op_sel:[1,0,0]
	s_waitcnt lgkmcnt(0)
	v_pk_fma_f32 v[38:39], v[34:35], v[84:85], v[38:39] op_sel_hi:[0,1,1]
	v_pk_mul_f32 v[186:187], v[34:35], v[84:85] op_sel_hi:[0,1]
	v_pk_mul_f32 v[174:175], v[34:35], v[78:79] op_sel:[1,0]
	v_pk_fma_f32 v[34:35], v[34:35], v[78:79], v[38:39] op_sel:[1,0,0]
	v_pk_mul_f32 v[178:179], v[36:37], v[86:87] op_sel_hi:[0,1]
	v_pk_fma_f32 v[34:35], v[36:37], v[86:87], v[34:35] op_sel_hi:[0,1,1]
	v_pk_fma_f32 v[34:35], v[36:37], v[80:81], v[34:35] op_sel:[1,0,0]
	v_pk_mul_f32 v[206:207], v[44:45], v[70:71] op_sel:[1,0]
	v_pk_mul_f32 v[182:183], v[40:41], v[76:77] op_sel:[1,0]
	v_pk_mul_f32 v[168:169], v[36:37], v[80:81] op_sel:[1,0]
	v_add_f32_e32 v170, v34, v35
	v_mov_b32_e32 v223, v224
	v_mov_b32_e32 v227, v222
